# static priority raise for waves 4-7 in D units and in the sample window (S) units
# baseline (speedup 1.0000x reference)
; DI f32x4 unpack4(v2u w) { return (f32x4){bflo(w.x), bfhi(w.x), bflo(w.y), bfhi(w.y)}; }
; DI float fexp2(float x) { return __builtin_amdgcn_exp2f(x); }
; DI void unit_sample_attn2(int u, const bf16* __restrict__ Q, const float* __restrict__ ckw, const float* __restrict__ cvw, const float* __restrict__ nkw, const float* __restrict__ nvw, const bf16* __restrict__ G, bf16* __restrict__ MIX, ...
;     ...
;     const int b = u >> 2, hq = u & 3, half = lane >> 5, hl = (lane >> 4) & 1, coff = hq * 128 + (lane & 31) * 4;
;     const float slope2 = fexp2(-(float)(hq * 2 + hl + 1)) * LOG2E;
;     const float* ck = ckw + (size_t)b * 2048 * 512 + coff; const float* cv = cvw + (size_t)b * 2048 * 512 + coff;
;     const float* nk = nkw + (size_t)b * 4 * 512 + coff;    const float* nv = nvw + (size_t)b * 4 * 512 + coff;
;     f32x4 q[4];
; #pragma unroll
;     for (int jj = 0; jj < 4; ++jj) q[jj] = unpack4(*(const v2u*)(Q + (size_t)(MP + b * 4 + jj) * 512 + coff));
;     const int j1 = wave & 3, sub = wave >> 2;
;     const f32x4 qs = (j1 == 0) ? q[0] : (j1 == 1) ? q[1] : (j1 == 2) ? q[2] : q[3];
; __global__ void __launch_bounds__(NT, 2) fwd(Args args) {
;     ...
;         for (int r2 = 0; r2 < ((SEQ_P2A & 1) ? 2 : 1); ++r2) for (;;) { const int u = __builtin_amdgcn_readfirstlane(q_next(ctl + CW_Q0 + (pass * 8 + r2) * 64, slot, tid)); if (u >= 512) break;
;             unit_sample_attn2(u, QB, args.in[3], args.in[4], out + O_SWK, out + O_SWV, GB, MIX, lds, tid, lane, wave); }
.LBB0_722:
	s_setprio 0
	s_waitcnt vmcnt(0)
	s_barrier
	s_and_saveexec_b64 s[2:3], s[56:57]
	s_cbranch_execz .LBB0_726
	v_mov_b32_e32 v4, s49
	s_nop 0
	ds_write_b32 v4, v227
.LBB0_726:
	s_or_b64 exec, exec, s[2:3]
	v_mov_b32_e32 v3, s49
	s_waitcnt lgkmcnt(0)
	s_barrier
	ds_read_b32 v3, v3
	s_mov_b64 s[2:3], -1
	s_waitcnt lgkmcnt(0)
	v_readfirstlane_b32 s0, v3
	s_cmpk_gt_i32 s0, 0x1ff
	s_cbranch_scc1 .LBB0_721
	s_cmp_lt_u32 s33, 4
	s_cbranch_scc1 .Lsprio_lo
	s_setprio 2
.Lsprio_lo:
	v_mov_b32_e32 v3, v0
	v_mov_b32_e32 v169, v182
	s_and_b32 s1, s0, 3
	v_lshlrev_b32_e32 v4, 2, v169
	s_lshl_b32 s38, s1, 7
	v_and_b32_e32 v164, 0x7c, v4
	s_and_b32 s2, s0, -4
	v_or_b32_e32 v4, s38, v164
	s_add_i32 s34, s2, 0x4000
	v_lshlrev_b32_e32 v6, 1, v4
	v_mov_b32_e32 v7, v2
	s_ashr_i32 s35, s34, 31
	s_ashr_i32 s3, s2, 31
	v_lshl_add_u64 v[6:7], s[78:79], 0, v[6:7]
	s_lshl_b64 s[6:7], s[34:35], 10
	s_lshl_b64 s[2:3], s[2:3], 10
	v_lshl_add_u64 v[8:9], v[6:7], 0, s[6:7]
	v_lshl_add_u64 v[6:7], v[6:7], 0, s[2:3]
	s_mov_b32 s2, 0x1000000
	v_add_co_u32_e32 v6, vcc, s2, v6
	global_load_dwordx2 v[8:9], v[8:9], off
	s_nop 0
	v_addc_co_u32_e32 v7, vcc, 0, v7, vcc
	global_load_dwordx2 v[10:11], v[6:7], off offset:1024
	global_load_dwordx2 v[12:13], v[6:7], off offset:2048
	s_nop 0
	global_load_dwordx2 v[6:7], v[6:7], off offset:3072
	s_cmp_lt_i32 s46, 1
	s_waitcnt vmcnt(3)
	v_and_b32_e32 v150, 0xffff0000, v8
	v_lshlrev_b32_e32 v151, 16, v9
	v_lshlrev_b32_e32 v152, 16, v8
	v_and_b32_e32 v153, 0xffff0000, v9
	s_waitcnt vmcnt(2)
	v_and_b32_e32 v146, 0xffff0000, v10
	v_lshlrev_b32_e32 v147, 16, v11
	v_lshlrev_b32_e32 v148, 16, v10
	v_and_b32_e32 v149, 0xffff0000, v11
	s_waitcnt vmcnt(1)
	v_and_b32_e32 v142, 0xffff0000, v12
	v_lshlrev_b32_e32 v143, 16, v13
	v_lshlrev_b32_e32 v144, 16, v12
	v_and_b32_e32 v145, 0xffff0000, v13
	s_waitcnt vmcnt(0)
	v_and_b32_e32 v138, 0xffff0000, v6
	v_lshlrev_b32_e32 v139, 16, v7
	v_lshlrev_b32_e32 v140, 16, v6
	v_and_b32_e32 v141, 0xffff0000, v7
	s_cbranch_scc1 .LBB0_730
	s_cmp_lg_u32 s46, 1
	s_cbranch_scc0 .LBB0_731
	s_mov_b64 s[2:3], s[52:53]
	v_cndmask_b32_e64 v161, v141, v145, s[2:3]
	v_cndmask_b32_e64 v160, v139, v143, s[2:3]
	v_cndmask_b32_e64 v159, v138, v142, s[2:3]
	v_cndmask_b32_e64 v158, v140, v144, s[2:3]
	s_branch .LBB0_732
